# P3: half of each XCD's workgroups start ~6 us later so the two groups' gate-loading seams do not coincide
# speedup vs baseline: 1.0088x; 1.0088x over previous
.LBB0_598:
	s_andn2_b64 vcc, exec, s[26:27]
	v_readlane_b32 s26, v241, 17
	v_readlane_b32 s27, v241, 18
	s_nop 1
	v_cndmask_b32_e64 v0, 0, 1, s[26:27]
	s_waitcnt lgkmcnt(0)
	v_cmp_ne_u32_e64 s[38:39], 1, v0
	s_cbranch_vccnz .LBB0_681
	s_mov_b64 s[26:27], s[96:97]
	v_mov_b32_e32 v0, v224
	s_and_b64 vcc, exec, s[38:39]
	v_readfirstlane_b32 s42, v0
	s_cbranch_vccnz .LBB0_629
	s_and_b32 s30, s2, 64
	s_cmp_eq_u32 s30, 0
	s_cbranch_scc1 .Lp3_nodelay
	s_sleep 127
	s_sleep 64
.Lp3_nodelay:
	v_lshlrev_b32_e32 v2, 4, v0
	v_add_u32_e32 v3, 0x2000, v2
	v_ashrrev_i32_e32 v4, 31, v3
	v_lshrrev_b32_e32 v4, 22, v4
	v_add_u32_e32 v4, v3, v4
	v_ashrrev_i32_e32 v10, 10, v4
	v_mul_i32_i24_e32 v4, 0x400, v10
	s_load_dwordx2 s[40:41], s[26:27], 0xa8
	v_sub_u32_e32 v3, v3, v4
	v_lshrrev_b32_e32 v4, 4, v3
	v_bitop3_b32 v3, v4, v3, 32 bitop3:0x6c
	v_ashrrev_i32_e32 v4, 31, v3
	v_lshrrev_b32_e32 v4, 26, v4
	s_mul_i32 s30, s86, 0x180000
	s_waitcnt lgkmcnt(0)
	s_add_u32 s8, s40, 0x5000000
	v_add_u32_e32 v4, v3, v4
	v_lshlrev_b32_e32 v5, 3, v10
	s_addc_u32 s9, s41, 0
	s_lshl_b64 s[26:27], s[30:31], 1
	v_ashrrev_i32_e32 v11, 6, v4
	v_and_b32_e32 v5, -16, v5
	s_add_u32 s13, s40, s26
	v_add_u32_e32 v5, v11, v5
	s_addc_u32 s16, s41, s27
	v_and_b32_e32 v6, 3, v11
	s_mov_b32 s27, 0x7fffe0
	v_lshrrev_b32_e32 v7, 2, v5
	v_lshlrev_b32_e32 v8, 1, v5
	v_and_b32_e32 v4, 0xc0, v4
	v_and_or_b32 v6, v5, s27, v6
	v_and_b32_e32 v7, 4, v7
	v_and_b32_e32 v8, 24, v8
	v_sub_u32_e32 v3, v3, v4
	v_or3_b32 v6, v6, v7, v8
	v_lshlrev_b32_e32 v7, 5, v10
	v_ashrrev_i16_sdwa v3, v225, sext(v3) dst_sel:DWORD dst_unused:UNUSED_PAD src0_sel:DWORD src1_sel:BYTE_0
	v_and_b32_e32 v12, 32, v7
	v_bfe_i32 v13, v3, 0, 16
	s_movk_i32 s26, 0x600
	v_mul_u32_u24_e32 v6, 0x600, v6
	v_add_u32_e32 v3, v12, v13
	v_mul_lo_u32 v4, v5, s26
	v_add_lshl_u32 v140, v6, v3, 1
	v_add_lshl_u32 v142, v3, v4, 1
	v_bfe_i32 v3, v0, 27, 1
	v_lshrrev_b32_e32 v3, 22, v3
	v_add_u32_e32 v3, v2, v3
	v_and_b32_e32 v3, 0xfffffc00, v3
	v_sub_u32_e32 v2, v2, v3
	v_lshrrev_b32_e32 v3, 4, v2
	v_bitop3_b32 v3, v3, v2, 32 bitop3:0x6c
	v_ashrrev_i32_e32 v2, 31, v2
	v_lshrrev_b32_e32 v2, 26, v2
	v_add_u32_e32 v2, v3, v2
	v_ashrrev_i32_e32 v14, 6, v2
	v_ashrrev_i32_e32 v2, 31, v0
	v_lshrrev_b32_e32 v2, 26, v2
	v_add_u32_e32 v2, v0, v2
	v_ashrrev_i32_e32 v15, 6, v2
	v_lshlrev_b32_e32 v2, 3, v15
	v_and_b32_e32 v2, -16, v2
	v_add_u32_e32 v2, v14, v2
	v_and_b32_e32 v4, 3, v14
	v_lshrrev_b32_e32 v5, 2, v2
	v_lshlrev_b32_e32 v6, 1, v2
	v_and_or_b32 v4, v2, s27, v4
	v_and_b32_e32 v5, 4, v5
	v_and_b32_e32 v6, 24, v6
	v_or3_b32 v4, v4, v5, v6
	v_lshlrev_b32_e32 v5, 5, v15
	s_add_u32 s13, s13, 0x2000000
	v_and_b32_e32 v16, 32, v5
	v_mul_i32_i24_e32 v5, 64, v14
	s_addc_u32 s16, s16, 0
	s_ashr_i32 s44, s42, 6
	v_sub_u32_e32 v3, v3, v5
	v_readlane_b32 s27, v241, 30
	s_ashr_i32 s43, s42, 8
	s_lshl_b32 s25, s44, 10
	v_ashrrev_i16_sdwa v3, v225, sext(v3) dst_sel:DWORD dst_unused:UNUSED_PAD src0_sel:DWORD src1_sel:BYTE_0
	v_mul_lo_u32 v2, v2, s26
	s_mul_i32 s26, s27, 0xc0000
	v_bfe_i32 v17, v3, 0, 16
	s_add_u32 s62, s13, s26
	s_mul_hi_i32 s26, s27, 0xc0000
	v_mul_u32_u24_e32 v4, 0x600, v4
	v_add_u32_e32 v3, v16, v17
	s_addc_u32 s63, s16, s26
	s_add_i32 s30, s25, 0
	v_add_lshl_u32 v144, v4, v3, 1
	s_add_i32 m0, s30, 0x10000
	v_add_lshl_u32 v146, v3, v2, 1
	global_load_lds_dwordx4 v144, s[62:63]
	s_add_i32 m0, s30, 0x12000
	s_add_u32 s26, s62, 0x60000
	global_load_lds_dwordx4 v140, s[62:63]
	s_addc_u32 s27, s63, 0
	s_add_i32 m0, s30, 0x14000
	v_mov_b32_e32 v145, v1
	global_load_lds_dwordx4 v144, s[26:27]
	s_add_i32 m0, s30, 0x16000
	v_mov_b32_e32 v141, v1
	global_load_lds_dwordx4 v140, s[26:27]
	v_readlane_b32 s26, v241, 37
	s_mov_b32 s28, s26
	s_mul_i32 s26, s26, 0xc0000
	s_add_u32 s60, s8, s26
	s_mul_hi_i32 s26, s28, 0xc0000
	s_addc_u32 s61, s9, s26
	s_add_i32 s55, s30, 0x2000
	v_readlane_b32 s27, v241, 38
	s_mov_b32 m0, s30
	s_add_u32 s26, s60, 0x60000
	global_load_lds_dwordx4 v146, s[60:61]
	s_mov_b32 m0, s55
	s_addc_u32 s27, s61, 0
	s_add_i32 s56, s30, 0x4000
	global_load_lds_dwordx4 v142, s[60:61]
	s_mov_b32 m0, s56
	s_add_i32 s57, s30, 0x6000
	global_load_lds_dwordx4 v146, s[26:27]
	s_mov_b32 m0, s57
	v_mov_b32_e32 v147, v1
	global_load_lds_dwordx4 v142, s[26:27]
	v_mov_b32_e32 v143, v1
	s_cmp_eq_u32 s43, 1
	v_lshl_add_u64 v[8:9], s[62:63], 0, v[144:145]
	v_lshl_add_u64 v[6:7], s[62:63], 0, v[140:141]
	v_lshl_add_u64 v[2:3], s[60:61], 0, v[146:147]
	s_cselect_b64 s[26:27], -1, 0
	s_cmp_lg_u32 s43, 1
	v_lshl_add_u64 v[4:5], s[60:61], 0, v[142:143]
	s_cbranch_scc1 .LBB0_602
	s_barrier
